# v014
# baseline (speedup 1.0000x reference)
; DEVI f32x4 mfma16(bf16x8 a, bf16x8 b, f32x4 c) { return __builtin_amdgcn_mfma_f32_16x16x32_bf16(a, b, c, 0, 0, 0); }
; template <bool SPLIT>
; DEVI void gemm_main(f32x4 (&acc)[4][4], const bf16_t* __restrict__ A, long lda, const bf16_t* __restrict__ B, long ldb, int K,
;                     int m0, int n0, char* lds, const float* __restrict__ ssq) {
;     ...
;   GSTAGE(lds, 0);
;   asm volatile("s_waitcnt vmcnt(0)" ::: "memory");
;   __syncthreads();
;   for (int kt = 0; kt < nt; ++kt) {
;     char* st = lds + (kt & 1) * 32768;
;     if (kt + 1 < nt) GSTAGE(lds + ((kt + 1) & 1) * 32768, kt + 1);
;     if (SPLIT) {
;       if (kt == 8) {
; #pragma unroll
;         for (int m = 0; m < 4; ++m)
; #pragma unroll
;           for (int j = 0; j < 4; ++j) {
;             const float* q = ssq + (long)(m0 + wr * 64 + m * 16 + fq * 4 + j) * 8;
;             f32x4 s0 = *(const f32x4*)q, s1 = *(const f32x4*)(q + 4);
;             float sa = (s0[0] + s0[1] + s0[2] + s0[3]) * (1.f / 512) + EPS, sb = (s1[0] + s1[1] + s1[2] + s1[3]) * (1.f / 512) + EPS;
;             float ratio = sqrtf(sb / sa);
; #pragma unroll
;             for (int n = 0; n < 4; ++n) acc[m][n][j] *= ratio;
;           }
;       }
;     }
; #pragma unroll
;     for (int kk = 0; kk < 2; ++kk) {
;       bf16x8 af[4], bfr[4];
;       const int co = ((kk * 4 + fq) ^ rsw) << 4;
; #pragma unroll
;       for (int m = 0; m < 4; ++m) af[m] = *(const bf16x8*)(st + a_rd + m * 2048 + co);
; #pragma unroll
;       for (int n = 0; n < 4; ++n) bfr[n] = *(const bf16x8*)(st + b_rd + n * 2048 + co);
; #pragma unroll
;       for (int m = 0; m < 4; ++m)
; #pragma unroll
;         for (int n = 0; n < 4; ++n) acc[m][n] = mfma16(af[m], bfr[n], acc[m][n]);
;     }
;     asm volatile("s_waitcnt vmcnt(0)" ::: "memory");
;     __syncthreads();
;   }
.LBB0_915:
	s_add_i32 s11, s10, 0xffff8000
	s_and_b32 s16, s11, 0x8000
	s_and_b32 s11, s10, 0x8000
	v_or_b32_e32 v0, s11, v184
	v_lshl_add_u64 v[82:83], v[72:73], 0, s[4:5]
	s_mov_b64 s[14:15], 0x2300080
	v_lshl_add_u64 v[78:79], v[70:71], 0, s[4:5]
	v_lshl_add_u64 v[86:87], v[82:83], 0, s[14:15]
	v_or_b32_e32 v77, 0x4000, v0
	v_readfirstlane_b32 s14, v0
	v_lshl_add_u64 v[80:81], v[78:79], 0, s[66:67]
	s_mov_b32 m0, s14
	v_readfirstlane_b32 s14, v77
	v_add_u32_e32 v77, 0x1000, v0
	global_load_lds_dwordx4 v[80:81], off
	s_mov_b32 m0, s14
	v_readfirstlane_b32 s14, v77
	global_load_lds_dwordx4 v[86:87], off
	v_lshl_add_u64 v[80:81], v[78:79], 0, s[96:97]
	s_mov_b32 m0, s14
	s_mov_b64 s[14:15], 0x2310080
	v_add_u32_e32 v77, 0x5000, v0
	global_load_lds_dwordx4 v[80:81], off
	v_lshl_add_u64 v[80:81], v[82:83], 0, s[14:15]
	v_readfirstlane_b32 s14, v77
	v_add_u32_e32 v77, 0x2000, v0
	s_mov_b32 m0, s14
	v_readfirstlane_b32 s14, v77
	global_load_lds_dwordx4 v[80:81], off
	v_lshl_add_u64 v[80:81], v[78:79], 0, s[64:65]
	s_mov_b32 m0, s14
	s_mov_b64 s[14:15], 0x2320080
	v_add_u32_e32 v77, 0x6000, v0
	global_load_lds_dwordx4 v[80:81], off
	v_lshl_add_u64 v[80:81], v[82:83], 0, s[14:15]
	v_readfirstlane_b32 s14, v77
	v_add_u32_e32 v77, 0x3000, v0
	s_mov_b32 m0, s14
	v_readfirstlane_b32 s14, v77
	global_load_lds_dwordx4 v[80:81], off
	v_lshl_add_u64 v[78:79], v[78:79], 0, s[54:55]
	s_mov_b32 m0, s14
	s_mov_b64 s[14:15], 0x2330080
	v_add_u32_e32 v0, 0x7000, v0
	global_load_lds_dwordx4 v[78:79], off
	v_lshl_add_u64 v[78:79], v[82:83], 0, s[14:15]
	v_readfirstlane_b32 s14, v0
	s_mov_b32 m0, s14
	v_add_u32_e32 v0, s16, v186
	global_load_lds_dwordx4 v[78:79], off
	v_or_b32_e32 v77, s16, v185
	v_add_u32_e32 v82, v0, v187
	ds_read_b128 v[78:81], v82
	ds_read_b128 v[86:89], v82 offset:2048
	ds_read_b128 v[90:93], v82 offset:4096
	ds_read_b128 v[94:97], v82 offset:6144
	v_add_u32_e32 v82, v77, v187
	ds_read_b128 v[98:101], v82 offset:16384
	ds_read_b128 v[102:105], v82 offset:18432
	ds_read_b128 v[106:109], v82 offset:20480
	ds_read_b128 v[110:113], v82 offset:22528
	v_add_u32_e32 v0, v0, v188
	ds_read_b128 v[114:117], v0
	ds_read_b128 v[118:121], v0 offset:2048
	ds_read_b128 v[122:125], v0 offset:4096
	ds_read_b128 v[126:129], v0 offset:6144
	v_add_u32_e32 v0, v77, v188
	ds_read_b128 v[130:133], v0 offset:16384
	ds_read_b128 v[134:137], v0 offset:18432
	ds_read_b128 v[138:141], v0 offset:20480
	ds_read_b128 v[242:245], v0 offset:22528
	s_waitcnt lgkmcnt(8)
	v_mfma_f32_16x16x32_bf16 v[62:65], v[78:81], v[98:101], v[62:65]
	s_add_u32 s4, s4, 0x80
	s_addc_u32 s5, s5, 0
	s_add_i32 s10, s10, 0x8000
	v_mfma_f32_16x16x32_bf16 v[58:61], v[78:81], v[102:105], v[58:61]
	s_cmpk_eq_i32 s4, 0x780
	v_mfma_f32_16x16x32_bf16 v[54:57], v[78:81], v[106:109], v[54:57]
	v_mfma_f32_16x16x32_bf16 v[50:53], v[78:81], v[110:113], v[50:53]
	v_mfma_f32_16x16x32_bf16 v[46:49], v[86:89], v[98:101], v[46:49]
	v_mfma_f32_16x16x32_bf16 v[42:45], v[86:89], v[102:105], v[42:45]
	v_mfma_f32_16x16x32_bf16 v[38:41], v[86:89], v[106:109], v[38:41]
	v_mfma_f32_16x16x32_bf16 v[34:37], v[86:89], v[110:113], v[34:37]
	v_mfma_f32_16x16x32_bf16 v[30:33], v[90:93], v[98:101], v[30:33]
	v_mfma_f32_16x16x32_bf16 v[26:29], v[90:93], v[102:105], v[26:29]
	v_mfma_f32_16x16x32_bf16 v[22:25], v[90:93], v[106:109], v[22:25]
	v_mfma_f32_16x16x32_bf16 v[18:21], v[90:93], v[110:113], v[18:21]
	v_mfma_f32_16x16x32_bf16 v[14:17], v[94:97], v[98:101], v[14:17]
	v_mfma_f32_16x16x32_bf16 v[10:13], v[94:97], v[102:105], v[10:13]
	v_mfma_f32_16x16x32_bf16 v[6:9], v[94:97], v[106:109], v[6:9]
	v_mfma_f32_16x16x32_bf16 v[2:5], v[94:97], v[110:113], v[2:5]
	s_waitcnt lgkmcnt(0)
	v_mfma_f32_16x16x32_bf16 v[62:65], v[114:117], v[130:133], v[62:65]
	s_waitcnt vmcnt(0)
	s_waitcnt vmcnt(0)
	s_barrier
	v_mfma_f32_16x16x32_bf16 v[58:61], v[114:117], v[134:137], v[58:61]
	v_mfma_f32_16x16x32_bf16 v[54:57], v[114:117], v[138:141], v[54:57]
	v_mfma_f32_16x16x32_bf16 v[50:53], v[114:117], v[242:245], v[50:53]
	v_mfma_f32_16x16x32_bf16 v[46:49], v[118:121], v[130:133], v[46:49]
	v_mfma_f32_16x16x32_bf16 v[42:45], v[118:121], v[134:137], v[42:45]
	v_mfma_f32_16x16x32_bf16 v[38:41], v[118:121], v[138:141], v[38:41]
	v_mfma_f32_16x16x32_bf16 v[34:37], v[118:121], v[242:245], v[34:37]
	v_mfma_f32_16x16x32_bf16 v[30:33], v[122:125], v[130:133], v[30:33]
	v_mfma_f32_16x16x32_bf16 v[26:29], v[122:125], v[134:137], v[26:29]
	v_mfma_f32_16x16x32_bf16 v[22:25], v[122:125], v[138:141], v[22:25]
	v_mfma_f32_16x16x32_bf16 v[18:21], v[122:125], v[242:245], v[18:21]
	v_mfma_f32_16x16x32_bf16 v[14:17], v[126:129], v[130:133], v[14:17]
	v_mfma_f32_16x16x32_bf16 v[10:13], v[126:129], v[134:137], v[10:13]
	v_mfma_f32_16x16x32_bf16 v[6:9], v[126:129], v[138:141], v[6:9]
	v_mfma_f32_16x16x32_bf16 v[2:5], v[126:129], v[242:245], v[2:5]
	s_cbranch_scc0 .LBB0_915
; DEVI bf16_t f2bf(float f) { return (bf16_t)(pk2(f, 0.f) & 0xffffu); }
; DEVI f32x4 mfma16(bf16x8 a, bf16x8 b, f32x4 c) { return __builtin_amdgcn_mfma_f32_16x16x32_bf16(a, b, c, 0, 0, 0); }
; template <bool SPLIT>
; DEVI void gemm_main(f32x4 (&acc)[4][4], const bf16_t* __restrict__ A, long lda, const bf16_t* __restrict__ B, long ldb, int K,
;                     int m0, int n0, char* lds, const float* __restrict__ ssq) {
;     ...
; #pragma unroll
;     for (int kk = 0; kk < 2; ++kk) {
;       bf16x8 af[4], bfr[4];
;       const int co = ((kk * 4 + fq) ^ rsw) << 4;
; #pragma unroll
;       for (int m = 0; m < 4; ++m) af[m] = *(const bf16x8*)(st + a_rd + m * 2048 + co);
; #pragma unroll
;       for (int n = 0; n < 4; ++n) bfr[n] = *(const bf16x8*)(st + b_rd + n * 2048 + co);
; #pragma unroll
;       for (int m = 0; m < 4; ++m)
; #pragma unroll
;         for (int n = 0; n < 4; ++n) acc[m][n] = mfma16(af[m], bfr[n], acc[m][n]);
;     }
;     asm volatile("s_waitcnt vmcnt(0)" ::: "memory");
;     __syncthreads();
;   }
; DEVI void phase9(const Params& p, int l, char* lds) {
;     ...
;     bf16_t* dst = (bf16_t*)(p.ws + (wc ? W_UP : W_U));
; #pragma unroll
;     for (int m = 0; m < 4; ++m)
; #pragma unroll
;       for (int j = 0; j < 4; ++j) {
;         const int row = m0 + wr * 64 + m * 16 + fq * 4 + j;
; #pragma unroll
;         for (int n = 0; n < 4; ++n) {
;           const int c = nt * 64 + n * 16 + fr;
;           dst[(long)row * DFF + c] = f2bf(acc[m][n][j]);
	v_add_u32_e32 v0, s11, v186
	v_add_u32_e32 v77, s11, v185
	v_add_u32_e32 v82, v0, v187
	ds_read_b128 v[70:73], v82
	ds_read_b128 v[78:81], v82 offset:2048
	ds_read_b128 v[86:89], v82 offset:4096
	ds_read_b128 v[90:93], v82 offset:6144
	v_add_u32_e32 v82, v77, v187
	ds_read_b128 v[94:97], v82 offset:16384
	ds_read_b128 v[98:101], v82 offset:18432
	ds_read_b128 v[102:105], v82 offset:20480
	ds_read_b128 v[106:109], v82 offset:22528
	v_add_u32_e32 v0, v0, v188
	s_waitcnt lgkmcnt(3)
	v_mfma_f32_16x16x32_bf16 v[62:65], v[70:73], v[94:97], v[62:65]
	s_waitcnt lgkmcnt(2)
	v_mfma_f32_16x16x32_bf16 v[58:61], v[70:73], v[98:101], v[58:61]
	s_waitcnt lgkmcnt(1)
	v_mfma_f32_16x16x32_bf16 v[54:57], v[70:73], v[102:105], v[54:57]
	s_waitcnt lgkmcnt(0)
	v_mfma_f32_16x16x32_bf16 v[50:53], v[70:73], v[106:109], v[50:53]
	v_mfma_f32_16x16x32_bf16 v[46:49], v[78:81], v[94:97], v[46:49]
	v_mfma_f32_16x16x32_bf16 v[42:45], v[78:81], v[98:101], v[42:45]
	v_mfma_f32_16x16x32_bf16 v[38:41], v[78:81], v[102:105], v[38:41]
	v_mfma_f32_16x16x32_bf16 v[34:37], v[78:81], v[106:109], v[34:37]
	v_mfma_f32_16x16x32_bf16 v[30:33], v[86:89], v[94:97], v[30:33]
	v_mfma_f32_16x16x32_bf16 v[26:29], v[86:89], v[98:101], v[26:29]
	v_mfma_f32_16x16x32_bf16 v[22:25], v[86:89], v[102:105], v[22:25]
	v_mfma_f32_16x16x32_bf16 v[18:21], v[86:89], v[106:109], v[18:21]
	v_mfma_f32_16x16x32_bf16 v[14:17], v[90:93], v[94:97], v[14:17]
	v_mfma_f32_16x16x32_bf16 v[10:13], v[90:93], v[98:101], v[10:13]
	v_mfma_f32_16x16x32_bf16 v[6:9], v[90:93], v[102:105], v[6:9]
	v_mfma_f32_16x16x32_bf16 v[2:5], v[90:93], v[106:109], v[2:5]
	ds_read_b128 v[70:73], v0
	ds_read_b128 v[78:81], v0 offset:2048
	ds_read_b128 v[86:89], v0 offset:4096
	ds_read_b128 v[90:93], v0 offset:6144
	v_add_u32_e32 v0, v77, v188
	ds_read_b128 v[94:97], v0 offset:16384
	ds_read_b128 v[98:101], v0 offset:18432
	ds_read_b128 v[102:105], v0 offset:20480
	ds_read_b128 v[106:109], v0 offset:22528
	s_waitcnt lgkmcnt(3)
	v_mfma_f32_16x16x32_bf16 v[62:65], v[70:73], v[94:97], v[62:65]
	v_add_u32_e32 v0, s9, v75
	s_waitcnt vmcnt(0)
	s_waitcnt lgkmcnt(0)
	v_mfma_f32_16x16x32_bf16 v[58:61], v[70:73], v[98:101], v[58:61]
	s_barrier
	v_mfma_f32_16x16x32_bf16 v[54:57], v[70:73], v[102:105], v[54:57]
	v_mfma_f32_16x16x32_bf16 v[50:53], v[70:73], v[106:109], v[50:53]
	v_mfma_f32_16x16x32_bf16 v[70:73], v[78:81], v[106:109], v[34:37]
	s_nop 2
	v_lshl_or_b32 v34, s8, 6, v74
	v_or_b32_e32 v36, v0, v76
	v_ashrrev_i32_e32 v35, 31, v34
	v_mfma_f32_16x16x32_bf16 v[46:49], v[78:81], v[94:97], v[46:49]
	v_cvt_pk_bf16_f32 v37, v62, s0
	v_mfma_f32_16x16x32_bf16 v[42:45], v[78:81], v[98:101], v[42:45]
	v_mfma_f32_16x16x32_bf16 v[38:41], v[78:81], v[102:105], v[38:41]
	v_mad_i64_i32 v[78:79], s[4:5], v36, s73, v[68:69]
	v_lshlrev_b64 v[80:81], 1, v[34:35]
	v_lshl_add_u64 v[78:79], v[78:79], 0, v[80:81]
	global_store_short v[78:79], v37, off
	v_cvt_pk_bf16_f32 v37, v58, s0
	global_store_short v[78:79], v37, off offset:32
	v_cvt_pk_bf16_f32 v37, v54, s0
	global_store_short v[78:79], v37, off offset:64
	v_cvt_pk_bf16_f32 v37, v50, s0
	global_store_short v[78:79], v37, off offset:96
	v_or_b32_e32 v37, 1, v36
	v_mad_i64_i32 v[78:79], s[4:5], v37, s73, v[68:69]
	v_cvt_pk_bf16_f32 v37, v63, s0
	v_lshl_add_u64 v[62:63], v[78:79], 0, v[80:81]
	global_store_short v[62:63], v37, off
	v_cvt_pk_bf16_f32 v37, v59, s0
	global_store_short v[62:63], v37, off offset:32
	v_cvt_pk_bf16_f32 v37, v55, s0
	global_store_short v[62:63], v37, off offset:64
	v_cvt_pk_bf16_f32 v37, v51, s0
	global_store_short v[62:63], v37, off offset:96
	v_or_b32_e32 v37, 2, v36
	v_mad_i64_i32 v[50:51], s[4:5], v37, s73, v[68:69]
	v_cvt_pk_bf16_f32 v37, v64, s0
	v_lshl_add_u64 v[50:51], v[50:51], 0, v[80:81]
	global_store_short v[50:51], v37, off
	v_cvt_pk_bf16_f32 v37, v60, s0
	global_store_short v[50:51], v37, off offset:32
	v_cvt_pk_bf16_f32 v37, v56, s0
	global_store_short v[50:51], v37, off offset:64
	v_cvt_pk_bf16_f32 v37, v52, s0
	global_store_short v[50:51], v37, off offset:96
	v_or_b32_e32 v37, 3, v36
	v_mad_i64_i32 v[50:51], s[4:5], v37, s73, v[68:69]
	v_cvt_pk_bf16_f32 v37, v65, s0
	v_lshl_add_u64 v[50:51], v[50:51], 0, v[80:81]
	global_store_short v[50:51], v37, off
	v_cvt_pk_bf16_f32 v37, v61, s0
	global_store_short v[50:51], v37, off offset:32
	v_cvt_pk_bf16_f32 v37, v57, s0
	global_store_short v[50:51], v37, off offset:64
	v_cvt_pk_bf16_f32 v37, v53, s0
	global_store_short v[50:51], v37, off offset:96
	v_or_b32_e32 v37, 16, v36
	v_mad_i64_i32 v[50:51], s[4:5], v37, s73, v[68:69]
	v_cvt_pk_bf16_f32 v37, v46, s0
	v_lshl_add_u64 v[50:51], v[50:51], 0, v[80:81]
	global_store_short v[50:51], v37, off
	v_cvt_pk_bf16_f32 v37, v42, s0
	global_store_short v[50:51], v37, off offset:32
	v_cvt_pk_bf16_f32 v37, v38, s0
	global_store_short v[50:51], v37, off offset:64
	v_cvt_pk_bf16_f32 v37, v70, s0
	global_store_short v[50:51], v37, off offset:96
; DEVI bf16_t f2bf(float f) { return (bf16_t)(pk2(f, 0.f) & 0xffffu); }
; DEVI void phase9(const Params& p, int l, char* lds) {
;     ...
;     bf16_t* dst = (bf16_t*)(p.ws + (wc ? W_UP : W_U));
; #pragma unroll
;     for (int m = 0; m < 4; ++m)
; #pragma unroll
;       for (int j = 0; j < 4; ++j) {
;         const int row = m0 + wr * 64 + m * 16 + fq * 4 + j;
; #pragma unroll
;         for (int n = 0; n < 4; ++n) {
;           const int c = nt * 64 + n * 16 + fr;
;           dst[(long)row * DFF + c] = f2bf(acc[m][n][j]);
;           if (wc == 0) {
;             if (row < TP) { if (row >= TP - 2) p.out[O_CONVP + ((long)l * 2 + (row - (TP - 2))) * DFF + c] = acc[m][n][j]; }
;             else { const int tt = (row - TP) & 63; if (tt >= 62) p.out[O_CONVS + (((long)l * 8 + ((row - TP) >> 6)) * 2 + (tt - 62)) * DFF + c] = acc[m][n][j]; }
	v_or_b32_e32 v37, 17, v36
	v_mad_i64_i32 v[50:51], s[4:5], v37, s73, v[68:69]
	v_cvt_pk_bf16_f32 v37, v47, s0
	v_lshl_add_u64 v[46:47], v[50:51], 0, v[80:81]
	global_store_short v[46:47], v37, off
	v_cvt_pk_bf16_f32 v37, v43, s0
	global_store_short v[46:47], v37, off offset:32
	v_cvt_pk_bf16_f32 v37, v39, s0
	global_store_short v[46:47], v37, off offset:64
	v_cvt_pk_bf16_f32 v37, v71, s0
	global_store_short v[46:47], v37, off offset:96
	v_or_b32_e32 v37, 18, v36
	v_mad_i64_i32 v[38:39], s[4:5], v37, s73, v[68:69]
	v_cvt_pk_bf16_f32 v37, v48, s0
	v_lshl_add_u64 v[38:39], v[38:39], 0, v[80:81]
	global_store_short v[38:39], v37, off
	v_cvt_pk_bf16_f32 v37, v44, s0
	global_store_short v[38:39], v37, off offset:32
	v_cvt_pk_bf16_f32 v37, v40, s0
	global_store_short v[38:39], v37, off offset:64
	v_cvt_pk_bf16_f32 v37, v72, s0
	global_store_short v[38:39], v37, off offset:96
	v_or_b32_e32 v37, 19, v36
	v_mad_i64_i32 v[38:39], s[4:5], v37, s73, v[68:69]
	v_cvt_pk_bf16_f32 v37, v49, s0
	v_lshl_add_u64 v[38:39], v[38:39], 0, v[80:81]
	global_store_short v[38:39], v37, off
	v_cvt_pk_bf16_f32 v37, v45, s0
	v_mfma_f32_16x16x32_bf16 v[18:21], v[86:89], v[106:109], v[18:21]
	global_store_short v[38:39], v37, off offset:32
	v_cvt_pk_bf16_f32 v37, v41, s0
	global_store_short v[38:39], v37, off offset:64
	v_mfma_f32_16x16x32_bf16 v[30:33], v[86:89], v[94:97], v[30:33]
	v_cvt_pk_bf16_f32 v37, v73, s0
	global_store_short v[38:39], v37, off offset:96
	v_or_b32_e32 v37, 32, v36
	v_mfma_f32_16x16x32_bf16 v[26:29], v[86:89], v[98:101], v[26:29]
	v_mad_i64_i32 v[38:39], s[4:5], v37, s73, v[68:69]
	v_lshl_add_u64 v[38:39], v[38:39], 0, v[80:81]
	v_mfma_f32_16x16x32_bf16 v[22:25], v[86:89], v[102:105], v[22:25]
	v_cvt_pk_bf16_f32 v18, v18, s0
	v_cvt_pk_bf16_f32 v30, v30, s0
	s_nop 2
	v_cvt_pk_bf16_f32 v26, v26, s0
	global_store_short v[38:39], v18, off offset:96
	v_or_b32_e32 v18, 33, v36
	v_cvt_pk_bf16_f32 v22, v22, s0
	global_store_short v[38:39], v30, off
	global_store_short v[38:39], v26, off offset:32
	global_store_short v[38:39], v22, off offset:64
	v_mad_i64_i32 v[38:39], s[4:5], v18, s73, v[68:69]
	v_cvt_pk_bf16_f32 v18, v31, s0
	v_lshl_add_u64 v[30:31], v[38:39], 0, v[80:81]
	global_store_short v[30:31], v18, off
	v_cvt_pk_bf16_f32 v18, v27, s0
	global_store_short v[30:31], v18, off offset:32
	v_cvt_pk_bf16_f32 v18, v23, s0
	global_store_short v[30:31], v18, off offset:64
	v_cvt_pk_bf16_f32 v18, v19, s0
	global_store_short v[30:31], v18, off offset:96
	v_or_b32_e32 v18, 34, v36
	v_mad_i64_i32 v[18:19], s[4:5], v18, s73, v[68:69]
	v_cvt_pk_bf16_f32 v22, v32, s0
	v_lshl_add_u64 v[18:19], v[18:19], 0, v[80:81]
	global_store_short v[18:19], v22, off
	v_cvt_pk_bf16_f32 v22, v28, s0
	global_store_short v[18:19], v22, off offset:32
	v_cvt_pk_bf16_f32 v22, v24, s0
	v_cvt_pk_bf16_f32 v20, v20, s0
	global_store_short v[18:19], v22, off offset:64
	global_store_short v[18:19], v20, off offset:96
	v_or_b32_e32 v18, 35, v36
	v_mad_i64_i32 v[18:19], s[4:5], v18, s73, v[68:69]
	v_cvt_pk_bf16_f32 v20, v33, s0
	v_lshl_add_u64 v[18:19], v[18:19], 0, v[80:81]
	global_store_short v[18:19], v20, off
	v_cvt_pk_bf16_f32 v20, v29, s0
	v_mfma_f32_16x16x32_bf16 v[2:5], v[90:93], v[106:109], v[2:5]
	global_store_short v[18:19], v20, off offset:32
	v_cvt_pk_bf16_f32 v20, v25, s0
	global_store_short v[18:19], v20, off offset:64
	v_mfma_f32_16x16x32_bf16 v[14:17], v[90:93], v[94:97], v[14:17]
	v_cvt_pk_bf16_f32 v20, v21, s0
	global_store_short v[18:19], v20, off offset:96
	v_or_b32_e32 v18, 48, v36
	v_mfma_f32_16x16x32_bf16 v[10:13], v[90:93], v[98:101], v[10:13]
	v_mad_i64_i32 v[18:19], s[4:5], v18, s73, v[68:69]
	v_lshl_add_u64 v[18:19], v[18:19], 0, v[80:81]
	v_mfma_f32_16x16x32_bf16 v[6:9], v[90:93], v[102:105], v[6:9]
	v_cvt_pk_bf16_f32 v2, v2, s0
	v_cvt_pk_bf16_f32 v14, v14, s0
	s_nop 2
	v_cvt_pk_bf16_f32 v10, v10, s0
	global_store_short v[18:19], v2, off offset:96
	v_or_b32_e32 v2, 49, v36
	v_cvt_pk_bf16_f32 v6, v6, s0
	global_store_short v[18:19], v14, off
	global_store_short v[18:19], v10, off offset:32
	global_store_short v[18:19], v6, off offset:64
	v_mad_i64_i32 v[18:19], s[4:5], v2, s73, v[68:69]
	v_cvt_pk_bf16_f32 v2, v15, s0
	v_lshl_add_u64 v[14:15], v[18:19], 0, v[80:81]
	global_store_short v[14:15], v2, off
	v_cvt_pk_bf16_f32 v2, v11, s0
	global_store_short v[14:15], v2, off offset:32
	v_cvt_pk_bf16_f32 v2, v7, s0
	global_store_short v[14:15], v2, off offset:64
	v_cvt_pk_bf16_f32 v2, v3, s0
	global_store_short v[14:15], v2, off offset:96
	v_or_b32_e32 v14, 50, v36
	v_mad_i64_i32 v[2:3], s[4:5], v14, s73, v[68:69]
	v_cmp_lt_i32_e32 vcc, s33, v14
	v_cvt_pk_bf16_f32 v6, v16, s0
	v_lshl_add_u64 v[10:11], v[2:3], 0, v[80:81]
	global_store_short v[10:11], v6, off
	s_and_saveexec_b64 s[4:5], s[6:7]
	s_xor_b64 s[4:5], exec, s[4:5]
	s_cbranch_execz .LBB0_918
	v_cvt_pk_bf16_f32 v2, v12, s0
	global_store_short v[10:11], v2, off offset:32
